# stack32 + deferred-weights work in P1: the 64 constant-partial jobs move from the workgroups that already have 5 transpose items per wave to the ones with 4 (balances the slowest path into the P1->P2
# speedup vs baseline: 1.0002x; 1.0002x over previous
.LBB0_423:
	s_cmp_eq_u32 s79, 0x60
	s_cselect_b32 s98, 64, 0
	s_sub_i32 s98, s78, s98
	v_lshl_or_b32 v10, s98, 1, v79
	v_cmp_gt_u32_e32 vcc, 64, v10
	s_and_saveexec_b64 s[2:3], vcc
	s_cbranch_execz .LBB0_428
	v_mov_b32_e32 v2, 0x7c00
	v_mov_b32_e32 v5, 0
	s_lshl_b32 s0, s79, 1
	v_lshl_or_b32 v2, v72, 2, v2
	v_mov_b32_e32 v3, v5
	v_lshl_or_b32 v11, s98, 1, v79
	s_mov_b64 s[10:11], 0
	s_movk_i32 s1, 0x9000
	s_movk_i32 s16, 0xa000
	s_movk_i32 s17, 0xb000
	s_movk_i32 s18, 0xc000
	s_movk_i32 s19, 0xd000
	s_movk_i32 s20, 0xe000
	s_movk_i32 s21, 0xf000
	s_mov_b64 s[12:13], 0x8000
